# v23 + static priority raise for waves 4-7 also in P2, scan and P3b
# baseline (speedup 1.0000x reference)
; #define LAS __attribute__((address_space(3)))
; DI int get_tid() { int t = threadIdx.x; asm volatile("" : "+v"(t)); return t; }
; DI void p2_unit(int chunk, const Params& p, LAS unsigned char* lds) {
;     const int tid = get_tid(), lane = tid & 63, wid = __builtin_amdgcn_readfirstlane(tid >> 6), r32 = lane & 31, hi = lane >> 5;
;     unsigned char* ws = p.ws;
;     bf16_t* proj = (bf16_t*)(ws + WS_PROJ); const float* aux = (const float*)(ws + WS_AUX);
;     const int b = chunk >> 7, n = chunk & 127, tok0 = chunk * 64;
;     LAS bf16_t* vT = (LAS bf16_t*)(lds + L2_VT); LAS bf16_t* kdT = (LAS bf16_t*)(lds + L2_KDT); LAS float* auxs = (LAS float*)(lds + L2_AUX); LAS float* decs = (LAS float*)(lds + L2_DEC);
; __global__ void __launch_bounds__(512, 2) fwd_megakernel(Params p) {
;     ...
;     for (int c = bx; c < MTOK / 64; c += G) p2_unit(c, p, lds);
.LBB0_345:
	s_or_b64 exec, exec, s[20:21]
	s_cmpk_lt_i32 s2, 0x200
	s_cselect_b64 s[0:1], -1, 0
	v_writelane_b32 v253, s0, 40
	s_waitcnt lgkmcnt(0)
	s_barrier
	v_readfirstlane_b32 s100, v208
	s_lshr_b32 s100, s100, 8
	s_cmp_lg_u32 s100, 0
	s_cbranch_scc0 .Lprio_p2_done
	s_setprio 1
.Lprio_p2_done:
	v_writelane_b32 v253, s1, 41
	s_add_u32 s0, s76, 0x2e00000
	v_writelane_b32 v253, s0, 42
	s_addc_u32 s0, s77, 0
	v_writelane_b32 v253, s0, 43
	s_add_u32 s0, s76, 0x2f00000
	v_writelane_b32 v253, s0, 44
	s_addc_u32 s0, s77, 0
	s_cmpk_gt_i32 s2, 0x1ff
	v_writelane_b32 v253, s0, 45
	s_cbranch_scc1 .LBB0_360
	s_lshl_b32 s52, s2, 6
	s_lshl_b64 s[0:1], s[2:3], 10
	s_add_u32 s0, s76, s0
	s_addc_u32 s1, s77, s1
	s_add_u32 s64, s0, 0x2f10000
	s_addc_u32 s65, s1, 0
	s_lshl_b64 s[66:67], s[10:11], 10
	s_movk_i32 s53, 0x1a00
	v_mov_b64_e32 v[64:65], s[14:15]
	v_mov_b32_e32 v67, 0
	s_movk_i32 s55, 0x1000
	s_mov_b32 s69, 0
	s_movk_i32 s58, 0x440
	v_and_b32_e32 v136, 64, v206
	s_mov_b32 s59, 0xbfb8aa3b
	s_mov_b32 s70, 0xb2a5705f
	s_mov_b32 s71, 0x42ce8ed0
	s_mov_b32 s72, 0xc2b17218
	s_mov_b32 s73, 0x7f800000
	s_mov_b32 s78, 0x3f2aaaab
	v_mov_b32_e32 v137, 0x3ecc95a3
	s_mov_b32 s79, 0x3f317218
	s_mov_b32 s81, 0x33800000
	v_add_u32_e32 v138, -1, v206
	v_add_u32_e32 v139, -2, v206
	v_add_u32_e32 v140, -4, v206
	v_add_u32_e32 v141, -8, v206
	v_add_u32_e32 v142, -16, v206
	v_subrev_u32_e32 v143, 32, v206
	s_mov_b32 s83, 0x800000
	s_mov_b32 s87, 0x3f317217
	s_movk_i32 s88, 0x240
	v_mov_b32_e32 v144, 0x7f800000
	v_mov_b32_e32 v68, 0x3f317218
	v_mov_b32_e32 v145, 0x41b17218
	s_mov_b32 s89, s2
	s_branch .LBB0_348

; #define GSYNC() xcd_barrier(xbar)
; DI void xcd_barrier(const XcdBarrier& b) {
;     asm volatile("s_waitcnt vmcnt(0)" ::: "memory");
;     __syncthreads();
;     if (threadIdx.x == 0) {
;         unsigned* bar = b.bar;
;         __builtin_amdgcn_s_waitcnt(0);
;         unsigned nloc = b.st[0], nx = b.st[1];
;         if (nloc == 0u) { xcd_barrier_complete(bar, b.x, nloc, nx); b.st[0] = nloc; b.st[1] = nx; }
; __global__ void __launch_bounds__(512, 2) fwd_megakernel(Params p) {
;     ...
;     GSYNC();
.LBB0_360:
	s_setprio 0
	s_waitcnt vmcnt(0)
	s_barrier
	s_mov_b64 s[20:21], exec
	v_readlane_b32 s0, v254, 16
	v_readlane_b32 s1, v254, 17
	s_and_b64 s[0:1], s[20:21], s[0:1]
	s_mov_b64 exec, s[0:1]
	s_cbranch_execz .LBB0_408
	s_add_i32 s0, 0, 0x22000
	v_mov_b32_e32 v0, s0
	s_waitcnt vmcnt(0) expcnt(0) lgkmcnt(0)
	ds_read_b32 v2, v0
	s_add_i32 s0, 0, 0x22004
	v_mov_b32_e32 v0, s0
	ds_read_b32 v0, v0
	s_waitcnt lgkmcnt(1)
	v_cmp_ne_u32_e32 vcc, 0, v2
	s_cbranch_vccnz .LBB0_376
	s_mov_b32 s0, 1
	v_mov_b32_e32 v16, 0
	s_branch .LBB0_364

; #define LAS __attribute__((address_space(3)))
; DI int get_tid() { int t = threadIdx.x; asm volatile("" : "+v"(t)); return t; }
; DI void gla_scan(const Params& p, int G, LAS unsigned char* lds) {
;     const float* dST = (const float*)(p.ws + WS_DST); const float* decay = (const float*)(p.ws + WS_DECAY); bf16_t* SpT = (bf16_t*)(p.ws + WS_SPT);
;     LAS float* dl = (LAS float*)lds;
;     const int tid = get_tid();
;     for (int e0 = blockIdx.x * 512; e0 < 16 * 8192; e0 += G * 512) {
;         const int e = e0 + tid, bh = e0 >> 13, vk = e & 8191, k = e & 63, b = bh >> 2, h = bh & 3;
.LBB0_432:
	v_readfirstlane_b32 s100, v208
	s_lshr_b32 s100, s100, 8
	s_cmp_lg_u32 s100, 0
	s_cbranch_scc0 .Lprio_p3_done
	s_setprio 1

; #define LAS __attribute__((address_space(3)))
; DI int get_tid() { int t = threadIdx.x; asm volatile("" : "+v"(t)); return t; }
; DI void gla_out_unit(int chunk, const Params& p, LAS unsigned char* lds) {
;     const int tid = get_tid(), lane = tid & 63, wid = __builtin_amdgcn_readfirstlane(tid >> 6), r32 = lane & 31, hi = lane >> 5;
;     const bf16_t* proj = (const bf16_t*)(p.ws + WS_PROJ);
;     const int b = chunk >> 7, n = chunk & 127, tok0 = chunk * 64;
;     LAS bf16_t* vT = (LAS bf16_t*)(lds + L2_VT);
;     const int h = wid >> 1, cb = wid & 1, bh = b * 4 + h, tok = tok0 + 32 * cb + r32;
; __global__ void __launch_bounds__(512, 2) fwd_megakernel(Params p) {
;     ...
;     for (int c = bx; c < MTOK / 64; c += G) gla_out_unit(c, p, lds);
.LBB0_615:
	s_or_b64 exec, exec, s[20:21]
	v_readlane_b32 s0, v253, 40
	v_readlane_b32 s1, v253, 41
	s_andn2_b64 vcc, exec, s[0:1]
	s_waitcnt lgkmcnt(0)
	v_cndmask_b32_e64 v0, 0, 1, s[0:1]
	v_cmp_ne_u32_e64 s[80:81], 1, v0
	s_barrier
	s_cbranch_vccnz .LBB0_624
	v_readfirstlane_b32 s100, v208
	s_lshr_b32 s100, s100, 8
	s_cmp_lg_u32 s100, 0
	s_cbranch_scc0 .Lprio_p3b_done
	s_setprio 1
.Lprio_p3b_done:
	s_lshl_b32 s0, s2, 6
	s_lshl_b32 s1, s2, 13
	s_lshl_b32 s4, s92, 13
	s_movk_i32 s5, 0x1a00
	v_mov_b64_e32 v[160:161], s[14:15]
	v_mov_b32_e32 v167, 0
	s_movk_i32 s6, 0x1000
	s_movk_i32 s7, 0x440
	v_mov_b32_e32 v211, 0x358637bd
	s_mov_b32 s12, s2
	s_branch .LBB0_618

; #define GSYNC() xcd_barrier(xbar)
; DI void xcd_barrier(const XcdBarrier& b) {
;     asm volatile("s_waitcnt vmcnt(0)" ::: "memory");
;     __syncthreads();
;     if (threadIdx.x == 0) {
;         unsigned* bar = b.bar;
;         __builtin_amdgcn_s_waitcnt(0);
;         unsigned nloc = b.st[0], nx = b.st[1];
;         if (nloc == 0u) { xcd_barrier_complete(bar, b.x, nloc, nx); b.st[0] = nloc; b.st[1] = nx; }
; __global__ void __launch_bounds__(512, 2) fwd_megakernel(Params p) {
;     ...
;     GSYNC();
.LBB0_624:
	s_setprio 0
	s_waitcnt vmcnt(0)
	s_barrier
	s_mov_b64 s[20:21], exec
	v_readlane_b32 s0, v254, 16
	v_readlane_b32 s1, v254, 17
	v_readlane_b32 s92, v253, 2
	s_and_b64 s[0:1], s[20:21], s[0:1]
	v_readlane_b32 s12, v253, 1
	v_readlane_b32 s93, v253, 3
	s_mov_b64 exec, s[0:1]
	s_cbranch_execz .LBB0_672
	s_add_i32 s0, 0, 0x22000
	v_mov_b32_e32 v0, s0
	s_waitcnt vmcnt(0) expcnt(0) lgkmcnt(0)
	ds_read_b32 v2, v0
	s_add_i32 s0, 0, 0x22004
	v_mov_b32_e32 v0, s0
	ds_read_b32 v0, v0
	s_waitcnt lgkmcnt(1)
	v_cmp_ne_u32_e32 vcc, 0, v2
	s_cbranch_vccnz .LBB0_640
	s_mov_b32 s0, 1
	v_mov_b32_e32 v16, 0
	s_branch .LBB0_628
